# attention outputs (rows handed to the next GEMM phase) stored cached instead of write-through; only final outputs stay write-through
# baseline (speedup 1.0000x reference)
; #define LAS __attribute__((address_space(3)))
; __device__ __forceinline__ unsigned pk2(float lo, float hi) { const f32x2_t v = {lo, hi}; const bf16x2_t b = __builtin_convertvector(v, bf16x2_t); return __builtin_bit_cast(unsigned, b); }
; __global__ void __launch_bounds__(NWAVES * 64, 2) mega(Args args) {
;     ...
;                 if (tid < 96) {
;                     const int j = tid >> 3, seg = tid & 7, g = j >> 2, qi = j & 3;
;                     const float l0 = lsel[qi], l1 = lsel[4 + qi], l2 = lsel[8 + qi], mx = fmaxf(l0, fmaxf(l1, l2));
;                     const float e0 = __expf(l0 - mx), e1 = __expf(l1 - mx), e2 = __expf(l2 - mx);
;                     const float w = (g == 0 ? e0 : (g == 1 ? e1 : e2)) * __builtin_amdgcn_rcpf(e0 + e1 + e2);
;                     const u32x4 v = *(const LAS u32x4*)(otile + j * 128 + seg * 16);
;                     u32x4 o; o.x = pk2(bflo(v.x) * w, bfhi(v.x) * w); o.y = pk2(bflo(v.y) * w, bfhi(v.y) * w); o.z = pk2(bflo(v.z) * w, bfhi(v.z) * w); o.w = pk2(bflo(v.w) * w, bfhi(v.w) * w);
;                     *(u32x4*)(CAT + ((size_t)MP + b * 4 + qi) * DM + (g * 4 + hs) * 64 + seg * 8) = o;
;                 }
.LBB0_1708:
	s_and_b32 s33, s86, 3
	s_waitcnt lgkmcnt(0)
	s_barrier
	s_and_saveexec_b64 s[6:7], s[44:45]
	s_cbranch_execz .LBB0_1585
	ds_read2_b32 v[0:1], v202 offset1:4
	ds_read_b32 v3, v202 offset:32
	ds_read_b128 v[4:7], v207 offset:40960
	s_and_b32 s0, s8, -4
	s_ashr_i32 s1, s0, 31
	v_mov_b32_e32 v155, v2
	s_waitcnt lgkmcnt(1)
	v_max3_f32 v8, v0, v1, v3
	v_sub_f32_e32 v0, v0, v8
	v_sub_f32_e32 v1, v1, v8
	v_mul_f32_e32 v0, 0x3fb8aa3b, v0
	v_mul_f32_e32 v1, 0x3fb8aa3b, v1
	v_sub_f32_e32 v3, v3, v8
	v_exp_f32_e32 v0, v0
	v_exp_f32_e32 v1, v1
	v_mul_f32_e32 v3, 0x3fb8aa3b, v3
	v_exp_f32_e32 v3, v3
	s_waitcnt lgkmcnt(0)
	v_and_b32_e32 v9, 0xffff0000, v4
	v_add_f32_e32 v8, v0, v1
	v_add_f32_e32 v8, v3, v8
	v_rcp_f32_e32 v8, v8
	v_cndmask_b32_e64 v1, v3, v1, s[48:49]
	v_cndmask_b32_e64 v0, v1, v0, s[46:47]
	v_mul_f32_e32 v0, v0, v8
	v_lshlrev_b32_e32 v8, 16, v4
	v_pk_mul_f32 v[8:9], v[0:1], v[8:9] op_sel_hi:[0,1]
	v_cvt_pk_bf16_f32 v4, v8, v9
	v_lshlrev_b32_e32 v8, 16, v5
	v_and_b32_e32 v9, 0xffff0000, v5
	v_pk_mul_f32 v[8:9], v[0:1], v[8:9] op_sel_hi:[0,1]
	v_cvt_pk_bf16_f32 v5, v8, v9
	v_lshlrev_b32_e32 v8, 16, v6
	v_and_b32_e32 v9, 0xffff0000, v6
	v_pk_mul_f32 v[8:9], v[0:1], v[8:9] op_sel_hi:[0,1]
	v_cvt_pk_bf16_f32 v6, v8, v9
	v_lshlrev_b32_e32 v8, 16, v7
	v_and_b32_e32 v9, 0xffff0000, v7
	v_pk_mul_f32 v[0:1], v[0:1], v[8:9] op_sel_hi:[0,1]
	v_cvt_pk_bf16_f32 v7, v0, v1
	v_lshl_add_u64 v[0:1], s[0:1], 0, v[150:151]
	v_lshlrev_b64 v[0:1], 11, v[0:1]
	v_lshl_or_b32 v8, s9, 6, v203
	v_lshl_add_u64 v[0:1], s[74:75], 0, v[0:1]
	v_ashrrev_i32_e32 v9, 31, v8
	v_lshl_add_u64 v[0:1], v[8:9], 1, v[0:1]
	v_lshl_add_u64 v[0:1], v[0:1], 0, v[154:155]
	global_store_dwordx4 v[0:1], v[4:7], off
	s_branch .LBB0_1585
